# P6 load balance via the v^T up-projection instead: workgroups 0-127 skip it (V^T base pointer for P7 still set), workgroups 128-255 run two v^T units
# speedup vs baseline: 1.0059x; 1.0049x over previous
.LBB0_873:
	s_cmpk_lt_u32 s54, 0x80
	s_cbranch_scc0 .Lv_light
	s_add_u32 s46, s88, 0x1c800000
	s_addc_u32 s47, s89, 0
	s_branch .LBB0_896
.Lv_light:
	s_sub_u32 s54, s54, 0x80
	s_movk_i32 s52, 0x80
	v_readlane_b32 s0, v254, 3
	s_add_u32 s46, s88, 0x1c800000
	v_mbcnt_lo_u32_b32 v0, -1, 0
	v_mbcnt_hi_u32_b32 v0, -1, v0
	s_addc_u32 s47, s89, 0
	v_or_b32_e32 v8, s0, v0
	s_andn2_b64 vcc, exec, s[6:7]
	v_readfirstlane_b32 s4, v8
	s_cbranch_vccnz .LBB0_900
	s_ashr_i32 s55, s54, 31
	s_lshr_b32 s0, s55, 29
	s_add_i32 s7, s54, s0
	s_and_b32 s0, s7, -8
	s_sub_i32 s5, s54, s0
	s_cmp_gt_i32 s5, -1
	s_cbranch_scc0 .LBB0_876
	s_lshl_b32 s6, s5, 5
	s_ashr_i32 s0, s7, 3
	s_cbranch_execz .LBB0_877
	s_branch .LBB0_878

.LBB0_896:
	s_mov_b32 s52, s90
	s_mov_b32 s54, s92
	s_mov_b32 s53, 0
	s_ashr_i32 s55, s54, 31
	s_waitcnt vmcnt(0)
	s_add_u32 s0, s88, 0x1600000
	s_addc_u32 s1, s89, 0
	s_lshl_b64 s[4:5], s[54:55], 7
	s_lshl_b64 s[6:7], s[52:53], 7
	s_movk_i32 s2, 0x80
	s_mov_b32 s8, 0x3b000000
	s_mov_b32 s3, 0x800000
	v_mov_b32_e32 v33, 0
	s_movk_i32 s9, 0x1400
	v_mov_b64_e32 v[34:35], s[72:73]
	s_mov_b32 s26, 0x8000
	s_mov_b32 s27, 0x10000
	s_mov_b32 s28, 0x18000
	v_mov_b32_e32 v124, 0x358637bd
	s_mov_b64 s[10:11], 0x1000
	s_barrier
	s_branch .LBB0_898
